# w_up items: the mod (sh2) loads for the c2 gemv are issued right after the tile loads instead of after the transpose
# speedup vs baseline: 1.0083x; 1.0083x over previous
; #define LAS __attribute__((address_space(3)))
; __device__ __forceinline__ int permcol(int n) { const int f = n < FF ? n : n - FF; return (f >> 7) * 256 + (f & 127) + (n < FF ? 0 : 128); }
; __device__ __forceinline__ void transpose_item(const float* W, int ldw, int k0, int n0, bf16* WT, int ldt, int drow0, int kd0, LAS float* scr, int lane) {
;     {
;         f32x4 t[8]; const int kq = lane >> 3, nq = lane & 7;
; #pragma unroll
;         for (int i = 0; i < 8; ++i) t[i] = __builtin_nontemporal_load((const f32x4*)(W + (size_t)(k0 + kq + 8 * i) * ldw + n0 + 4 * nq));
; #pragma unroll
;         for (int i = 0; i < 8; ++i) { LAS float* d = scr + (kq + 8 * i) * 33 + 4 * nq; d[0] = t[i][0]; d[1] = t[i][1]; d[2] = t[i][2]; d[3] = t[i][3]; } }
; __global__ void __launch_bounds__(NWAVES * 64, 2) fwd(Args a) {
;     ...
;             else if (it < I2) { const int r = it - I1, kb = r / 176, nb = r % 176; transpose_item(a.in[I_WUP], FF2, 64 * kb, 32 * nb, WupT, D, permcol(32 * nb), 64 * kb, scr, lane);
;                 LAS float* sb2 = scr + 64 * 33 + 16;
; #pragma unroll
;                 for (int b = 0; b < NBATCH; ++b) sb2[lane * 12 + b] = modv(macc, b_ada, b, 3 * D + 64 * kb + lane);
.LBB0_86:
	s_andn2_b64 vcc, exec, s[0:1]
	s_cbranch_vccnz .LBB0_90
	s_add_i32 s0, s33, 0xfb00
	s_and_b32 s1, s0, 0xffff
	s_mul_i32 s1, s1, 0xba2f
	s_lshr_b32 s8, s1, 23
	s_mul_i32 s1, s8, 0xb0
	s_sub_i32 s0, s0, s1
	s_lshl_b32 s6, s0, 5
	s_and_b32 s6, s6, 0xffe0
	s_lshl_b32 s1, s8, 6
	s_and_b32 s0, s0, 0xffff
	s_add_i32 s9, s6, 0xfffff500
	s_cmpk_lt_u32 s0, 0x58
	v_or_b32_e32 v2, s1, v27
	s_cselect_b32 s9, s6, s9
	s_cselect_b32 s0, 0, 0x80
	s_lshl_b32 s6, s6, 2
	v_mul_u32_u24_e32 v2, 0x1600, v2
	v_lshl_add_u64 v[14:15], v[6:7], 0, s[6:7]
	v_lshlrev_b32_e32 v2, 2, v2
	v_lshl_add_u64 v[58:59], v[14:15], 0, v[2:3]
	s_mov_b32 s6, 0x2c000
	v_add_co_u32_e32 v18, vcc, s6, v58
	s_mov_b32 s6, 0x58000
	s_nop 0
	v_addc_co_u32_e32 v19, vcc, 0, v59, vcc
	v_add_co_u32_e32 v22, vcc, s6, v58
	s_mov_b32 s6, 0x84000
	s_nop 0
	v_addc_co_u32_e32 v23, vcc, 0, v59, vcc
	v_add_co_u32_e32 v42, vcc, s6, v58
	s_mov_b32 s6, 0xb0000
	s_nop 0
	v_addc_co_u32_e32 v43, vcc, 0, v59, vcc
	v_add_co_u32_e32 v46, vcc, s6, v58
	s_mov_b32 s6, 0xdc000
	s_nop 0
	v_addc_co_u32_e32 v47, vcc, 0, v59, vcc
	v_add_co_u32_e32 v50, vcc, s6, v58
	global_load_dwordx4 v[14:17], v[58:59], off nt
	s_nop 0
	global_load_dwordx4 v[18:21], v[18:19], off nt
	v_addc_co_u32_e32 v51, vcc, 0, v59, vcc
	global_load_dwordx4 v[22:25], v[22:23], off nt
	s_nop 0
	global_load_dwordx4 v[42:45], v[42:43], off nt
	s_nop 0
	global_load_dwordx4 v[46:49], v[46:47], off nt
	s_nop 0
	global_load_dwordx4 v[50:53], v[50:51], off nt
	s_mov_b32 s6, 0x108000
	v_add_co_u32_e32 v54, vcc, s6, v58
	s_mov_b32 s6, 0x134000
	s_nop 0
	v_addc_co_u32_e32 v55, vcc, 0, v59, vcc
	global_load_dwordx4 v[54:57], v[54:55], off nt
	v_add_co_u32_e32 v58, vcc, s6, v58
	v_add_u32_e32 v2, v28, v29
	s_nop 0
	v_addc_co_u32_e32 v59, vcc, 0, v59, vcc
	global_load_dwordx4 v[58:61], v[58:59], off nt
	v_add_lshl_u32 v134, v26, s1, 2
	v_mov_b32_e32 v135, 0
	global_load_dword v120, v134, s[46:47]
	global_load_dword v122, v134, s[72:73]
	v_lshl_add_u64 v[132:133], s[72:73], 0, v[134:135]
	v_add_co_u32_e32 v136, vcc, s24, v132
	s_nop 1
	v_addc_co_u32_e32 v137, vcc, 0, v133, vcc
	v_add_co_u32_e32 v138, vcc, s25, v132
	s_nop 1
	v_addc_co_u32_e32 v139, vcc, 0, v133, vcc
	v_add_co_u32_e32 v140, vcc, s26, v132
	s_nop 1
	v_addc_co_u32_e32 v141, vcc, 0, v133, vcc
	v_add_co_u32_e32 v142, vcc, s27, v132
	s_nop 1
	v_addc_co_u32_e32 v143, vcc, 0, v133, vcc
	v_add_co_u32_e32 v144, vcc, s28, v132
	s_nop 1
	v_addc_co_u32_e32 v145, vcc, 0, v133, vcc
	v_add_co_u32_e32 v146, vcc, s29, v132
	s_nop 1
	v_addc_co_u32_e32 v147, vcc, 0, v133, vcc
	v_add_co_u32_e32 v148, vcc, s30, v132
	s_nop 1
	v_addc_co_u32_e32 v149, vcc, 0, v133, vcc
	v_add_co_u32_e32 v150, vcc, s31, v132
	s_nop 1
	v_addc_co_u32_e32 v151, vcc, 0, v133, vcc
	v_add_co_u32_e32 v152, vcc, 0x36000, v132
	s_nop 1
	v_addc_co_u32_e32 v153, vcc, 0, v133, vcc
	global_load_dword v123, v[136:137], off
	global_load_dword v124, v[138:139], off
	global_load_dword v125, v[140:141], off
	global_load_dword v126, v[142:143], off
	global_load_dword v127, v[144:145], off
	global_load_dword v128, v[146:147], off
	global_load_dword v129, v[148:149], off
	global_load_dword v130, v[150:151], off
	global_load_dword v131, v[152:153], off
	v_add_u32_e32 v41, 0x420, v2
	v_add_u32_e32 v62, 0x428, v2
	v_add_u32_e32 v63, 0x840, v2
	v_add_u32_e32 v64, 0x848, v2
	v_add_u32_e32 v65, 0xc60, v2
	v_add_u32_e32 v66, 0xc68, v2
	v_add_u32_e32 v67, 0x1080, v2
	v_add_u32_e32 v68, 0x1088, v2
	v_add_u32_e32 v69, 0x14a0, v2
	v_add_u32_e32 v70, 0x14a8, v2
	v_add_u32_e32 v71, 0x18c0, v2
	v_add_u32_e32 v72, 0x18c8, v2
	v_add_u32_e32 v73, 0x1ce0, v2
	v_add_u32_e32 v74, 0x1ce8, v2
	s_lshl_b32 s6, s9, 1
	s_and_b32 s10, s9, 0x60
	s_and_b32 s6, s6, 0x7fffff00
	s_or_b32 s10, s10, s0
	s_or_b32 s0, s10, s6
	s_lshr_b32 s6, s9, 3
	s_and_b32 s6, s6, 0x1ffffff0
	s_add_i32 s6, s6, s8
	s_lshl_b64 s[8:9], s[6:7], 15
	s_add_u32 s8, s85, s8
	s_addc_u32 s9, s89, s9
	s_waitcnt vmcnt(7)
	ds_write2_b32 v2, v14, v15 offset1:1
	ds_write2_b32 v2, v16, v17 offset0:2 offset1:3
	s_waitcnt vmcnt(6)
	ds_write2_b32 v41, v18, v19 offset1:1
	ds_write2_b32 v62, v20, v21 offset1:1
	s_waitcnt vmcnt(5)
	ds_write2_b32 v63, v22, v23 offset1:1
	ds_write2_b32 v64, v24, v25 offset1:1
	s_waitcnt vmcnt(4)
	ds_write2_b32 v65, v42, v43 offset1:1
	ds_write2_b32 v66, v44, v45 offset1:1
	s_waitcnt vmcnt(3)
	ds_write2_b32 v67, v46, v47 offset1:1
	ds_write2_b32 v68, v48, v49 offset1:1
	s_waitcnt vmcnt(2)
	ds_write2_b32 v69, v50, v51 offset1:1
	ds_write2_b32 v70, v52, v53 offset1:1
	s_waitcnt vmcnt(1)
	ds_write2_b32 v71, v54, v55 offset1:1
	ds_write2_b32 v72, v56, v57 offset1:1
	s_waitcnt vmcnt(0)
	ds_write2_b32 v73, v58, v59 offset1:1
	ds_write2_b32 v74, v60, v61 offset1:1
	s_waitcnt lgkmcnt(0)
	ds_read2_b32 v[18:19], v34 offset1:8
	ds_read2_b32 v[20:21], v34 offset0:33 offset1:41
	ds_read2_b32 v[22:23], v34 offset0:66 offset1:74
	ds_read2_b32 v[24:25], v34 offset0:99 offset1:107
	ds_read2_b32 v[42:43], v34 offset0:132 offset1:140
	s_waitcnt lgkmcnt(4)
	v_bfe_u32 v2, v18, 16, 1
	s_waitcnt lgkmcnt(3)
	v_bfe_u32 v14, v20, 16, 1
	v_add3_u32 v2, v18, v2, s18
	ds_read2_b32 v[44:45], v34 offset0:165 offset1:173
	s_waitcnt lgkmcnt(3)
	v_bfe_u32 v15, v22, 16, 1
	v_add3_u32 v14, v20, v14, s18
	v_lshrrev_b32_e32 v2, 16, v2
	v_add3_u32 v15, v22, v15, s18
	v_and_or_b32 v14, v14, s19, v2
	s_waitcnt lgkmcnt(2)
; #define LAS __attribute__((address_space(3)))
; __device__ __forceinline__ unsigned pk2(float lo, float hi) { return f2bf(lo) | (f2bf(hi) << 16); }
; __device__ __forceinline__ size_t blk_off(int row, int col, int K) { return ((size_t)((row >> 8) * (K >> 6) + (col >> 6)) << 14) + (size_t)(((row & 255) << 6) + (col & 63)); }
; __device__ __forceinline__ void transpose_item(const float* W, int ldw, int k0, int n0, bf16* WT, int ldt, int drow0, int kd0, LAS float* scr, int lane) {
;     ...
;     for (int j = 0; j < 4; ++j) { const int n = (lane >> 3) + 8 * j; const LAS float* s = scr + (8 * c) * 33 + n;
;         v4u o; o.x = pk2(s[0 * 33], s[1 * 33]); o.y = pk2(s[2 * 33], s[3 * 33]); o.z = pk2(s[4 * 33], s[5 * 33]); o.w = pk2(s[6 * 33], s[7 * 33]);
;         *(v4u*)(WT + blk_off(drow0 + n, kd0 + 8 * c, ldt)) = o; }
; __global__ void __launch_bounds__(NWAVES * 64, 2) fwd(Args a) {
;     ...
;                 for (int b = 0; b < NBATCH; ++b) sb2[lane * 12 + b] = modv(macc, b_ada, b, 3 * D + 64 * kb + lane);
	v_bfe_u32 v2, v24, 16, 1
	ds_read2_b32 v[46:47], v34 offset0:198 offset1:206
	v_lshrrev_b32_e32 v15, 16, v15
	v_add3_u32 v2, v24, v2, s18
	ds_read2_b32 v[48:49], v34 offset0:231 offset1:239
	v_and_or_b32 v15, v2, s19, v15
	s_waitcnt lgkmcnt(3)
	v_bfe_u32 v2, v42, 16, 1
	v_add3_u32 v2, v42, v2, s18
	s_waitcnt lgkmcnt(2)
	v_bfe_u32 v16, v44, 16, 1
	v_lshrrev_b32_e32 v2, 16, v2
	v_add3_u32 v16, v44, v16, s18
	v_and_or_b32 v16, v16, s19, v2
	s_waitcnt lgkmcnt(1)
	v_bfe_u32 v2, v46, 16, 1
	v_add3_u32 v2, v46, v2, s18
	s_waitcnt lgkmcnt(0)
	v_bfe_u32 v17, v48, 16, 1
	v_lshrrev_b32_e32 v2, 16, v2
	v_add3_u32 v17, v48, v17, s18
	v_and_or_b32 v17, v17, s19, v2
	v_or_b32_e32 v2, s10, v27
	v_lshlrev_b32_e32 v41, 1, v33
	v_lshl_or_b32 v2, v2, 7, v41
	global_store_dwordx4 v2, v[14:17], s[8:9]
	v_bfe_u32 v2, v19, 16, 1
	v_add3_u32 v2, v19, v2, s18
	v_bfe_u32 v14, v21, 16, 1
	v_lshrrev_b32_e32 v2, 16, v2
	v_add3_u32 v14, v21, v14, s18
	v_and_or_b32 v14, v14, s19, v2
	v_bfe_u32 v2, v23, 16, 1
	v_add3_u32 v2, v23, v2, s18
	v_bfe_u32 v15, v25, 16, 1
	v_lshrrev_b32_e32 v2, 16, v2
	v_add3_u32 v15, v25, v15, s18
	v_and_or_b32 v15, v15, s19, v2
	v_bfe_u32 v2, v43, 16, 1
	v_add3_u32 v2, v43, v2, s18
	v_bfe_u32 v16, v45, 16, 1
	v_lshrrev_b32_e32 v2, 16, v2
	v_add3_u32 v16, v45, v16, s18
	v_and_or_b32 v16, v16, s19, v2
	v_bfe_u32 v2, v47, 16, 1
	ds_read2_b32 v[18:19], v34 offset0:16 offset1:24
	v_add3_u32 v2, v47, v2, s18
	v_bfe_u32 v17, v49, 16, 1
	ds_read2_b32 v[20:21], v34 offset0:49 offset1:57
	v_lshrrev_b32_e32 v2, 16, v2
	v_add3_u32 v17, v49, v17, s18
	v_and_or_b32 v17, v17, s19, v2
	v_or_b32_e32 v2, s10, v30
	ds_read2_b32 v[22:23], v34 offset0:82 offset1:90
	v_lshl_or_b32 v2, v2, 7, v41
	ds_read2_b32 v[24:25], v34 offset0:115 offset1:123
	global_store_dwordx4 v2, v[14:17], s[8:9]
	s_waitcnt lgkmcnt(3)
	v_bfe_u32 v2, v18, 16, 1
	v_add3_u32 v2, v18, v2, s18
	s_waitcnt lgkmcnt(2)
	v_bfe_u32 v14, v20, 16, 1
	ds_read2_b32 v[42:43], v34 offset0:148 offset1:156
	v_lshrrev_b32_e32 v2, 16, v2
	v_add3_u32 v14, v20, v14, s18
	ds_read2_b32 v[44:45], v34 offset0:181 offset1:189
	v_and_or_b32 v14, v14, s19, v2
	s_waitcnt lgkmcnt(3)
	v_bfe_u32 v2, v22, 16, 1
	v_add3_u32 v2, v22, v2, s18
	s_waitcnt lgkmcnt(2)
	v_bfe_u32 v15, v24, 16, 1
	ds_read2_b32 v[46:47], v34 offset0:214 offset1:222
	v_lshrrev_b32_e32 v2, 16, v2
	v_add3_u32 v15, v24, v15, s18
	ds_read2_b32 v[48:49], v34 offset0:247 offset1:255
	v_and_or_b32 v15, v15, s19, v2
	s_waitcnt lgkmcnt(3)
	v_bfe_u32 v2, v42, 16, 1
	v_add3_u32 v2, v42, v2, s18
	s_waitcnt lgkmcnt(2)
	v_bfe_u32 v16, v44, 16, 1
	v_lshrrev_b32_e32 v2, 16, v2
	v_add3_u32 v16, v44, v16, s18
	v_and_or_b32 v16, v16, s19, v2
	s_waitcnt lgkmcnt(1)
	v_bfe_u32 v2, v46, 16, 1
	v_add3_u32 v2, v46, v2, s18
	s_waitcnt lgkmcnt(0)
	v_bfe_u32 v17, v48, 16, 1
	v_lshrrev_b32_e32 v2, 16, v2
	v_add3_u32 v17, v48, v17, s18
	v_and_or_b32 v17, v17, s19, v2
	v_or_b32_e32 v2, s10, v31
	v_lshlrev_b32_e32 v2, 6, v2
	v_and_or_b32 v2, v2, s23, v33
	v_lshlrev_b32_e32 v2, 1, v2
	global_store_dwordx4 v2, v[14:17], s[8:9]
	v_bfe_u32 v2, v19, 16, 1
	v_add3_u32 v2, v19, v2, s18
	v_bfe_u32 v14, v21, 16, 1
	v_lshrrev_b32_e32 v2, 16, v2
	v_add3_u32 v14, v21, v14, s18
	v_and_or_b32 v14, v14, s19, v2
	v_bfe_u32 v2, v23, 16, 1
	v_add3_u32 v2, v23, v2, s18
	v_bfe_u32 v15, v25, 16, 1
	v_lshrrev_b32_e32 v2, 16, v2
	v_add3_u32 v15, v25, v15, s18
	v_and_or_b32 v15, v15, s19, v2
	v_bfe_u32 v2, v43, 16, 1
	v_add3_u32 v2, v43, v2, s18
	v_bfe_u32 v16, v45, 16, 1
	v_lshrrev_b32_e32 v2, 16, v2
	v_add3_u32 v16, v45, v16, s18
	v_and_or_b32 v16, v16, s19, v2
	v_bfe_u32 v2, v47, 16, 1
	v_add3_u32 v2, v47, v2, s18
	v_bfe_u32 v17, v49, 16, 1
	v_lshrrev_b32_e32 v2, 16, v2
	v_add3_u32 v17, v49, v17, s18
	v_and_or_b32 v17, v17, s19, v2
	v_or_b32_e32 v2, s10, v32
	v_lshl_or_b32 v2, v2, 7, v41
	global_store_dwordx4 v2, v[14:17], s[8:9]
	v_add_lshl_u32 v2, v26, s1, 2
	s_waitcnt lgkmcnt(0)
	v_lshl_add_u64 v[14:15], s[72:73], 0, v[2:3]
	v_add_co_u32_e32 v20, vcc, s24, v14
	v_mov_b32_e32 v2, 0
	s_nop 0
	v_addc_co_u32_e32 v21, vcc, 0, v15, vcc
	v_add_co_u32_e32 v22, vcc, s25, v14
	s_mov_b32 s1, 0
	s_nop 0
	v_addc_co_u32_e32 v23, vcc, 0, v15, vcc
	v_add_co_u32_e32 v24, vcc, s26, v14
	s_nop 1
	v_addc_co_u32_e32 v25, vcc, 0, v15, vcc
	v_add_co_u32_e32 v42, vcc, s27, v14
	s_nop 1
	v_addc_co_u32_e32 v43, vcc, 0, v15, vcc
	v_add_co_u32_e32 v44, vcc, s28, v14
	s_nop 1
	v_addc_co_u32_e32 v45, vcc, 0, v15, vcc
	v_add_co_u32_e32 v46, vcc, s29, v14
	s_nop 1
	v_addc_co_u32_e32 v47, vcc, 0, v15, vcc
	v_add_co_u32_e32 v48, vcc, s30, v14
	s_nop 1
	v_addc_co_u32_e32 v49, vcc, 0, v15, vcc
	v_add_co_u32_e32 v50, vcc, s31, v14
	s_nop 1
	v_addc_co_u32_e32 v51, vcc, 0, v15, vcc
	v_add_co_u32_e32 v14, vcc, 0x36000, v14
	s_nop 0
	s_nop 0
	s_nop 0
	v_addc_co_u32_e32 v15, vcc, 0, v15, vcc
	s_waitcnt vmcnt(4)
	v_pk_add_f32 v[14:15], v[122:123], v[120:121] op_sel_hi:[1,0]
	v_pk_add_f32 v[16:17], v[124:125], v[120:121] op_sel_hi:[1,0]
	ds_write_b128 v37, v[14:17] offset:8512
	v_pk_add_f32 v[14:15], v[126:127], v[120:121] op_sel_hi:[1,0]
	v_pk_add_f32 v[16:17], v[128:129], v[120:121] op_sel_hi:[1,0]
	ds_write_b128 v37, v[14:17] offset:8528
	v_mov_b32_e32 v16, 0
	v_mov_b32_e32 v17, v2
	v_pk_add_f32 v[14:15], v[130:131], v[120:121] op_sel_hi:[1,0]
	ds_write_b64 v37, v[14:15] offset:8544
	s_waitcnt lgkmcnt(0)
	v_mov_b32_e32 v18, v35
	v_mov_b32_e32 v14, 0
	v_mov_b32_e32 v15, v2
